# MLA item order: the 4 workgroups of an XCD that share a (batch, head) take adjacent query-tile pairs (4*XCD + 0..3) so both their K/V streams stay within a few tiles of each other in L2
# speedup vs baseline: 1.0081x; 1.0074x over previous
; #define LAS __attribute__((address_space(3)))
; __global__ void __launch_bounds__(512) fwd_mega(Args a) {
;     ...
;         for (int it = vcu; it < 1024; it += G) { const int bh = it >> 5, s = it & 31;
;             att::attn_unit<true>(P, bh >> 4, bh & 15, 63 - s, (LAS char*)lds);
;             att::attn_unit<true>(P, bh >> 4, bh & 15, s, (LAS char*)lds); }
.Lm16_unit:
	s_and_b32 s33, s28, 7
	s_lshl_b32 s33, s33, 2
	s_bfe_u32 s37, s28, 0x20003
	s_or_b32 s33, s33, s37
	s_cmp_eq_u32 s29, 0
	s_cbranch_scc0 .Lm16_qb_ok
	s_sub_u32 s33, 63, s33
